# out-proj unit: panel acquire issued before the arrival-counter poll; row-statistics exchange (sc1 stores + sc1 loads) no longer issues a redundant L1 invalidate
# speedup vs baseline: 1.0363x; 1.0026x over previous
.LBB0_900:
	v_mov_b32_e32 v2, 0
	v_mov_b32_e32 v3, 0x4000
	global_load_dword v164, v2, s[82:83] sc1
	global_load_dword v165, v3, s[82:83] offset:512 sc1
	s_ashr_i32 s12, s64, 2
	s_lshl_b32 s0, s64, 2
	s_andn2_b32 s12, s12, 31
	s_and_b32 s13, s0, 28
	s_or_b32 s0, s12, s13
	s_bfe_u32 s14, s64, 0x20005
	s_or_b32 s6, s0, s14
	s_lshl_b32 s8, s6, 6
	v_mov_b32_e32 v6, v0
	s_ashr_i32 s9, s8, 31
	s_nop 0
	v_readfirstlane_b32 s19, v6
	s_mov_b64 s[0:1], exec
	v_readlane_b32 s2, v254, 6
	v_readlane_b32 s3, v254, 7
	s_and_b64 s[2:3], s[0:1], s[2:3]
	s_mov_b64 exec, s[2:3]
	s_cbranch_execz .LBB0_917
	s_lshl_b64 s[2:3], s[8:9], 2
	s_add_u32 s2, s82, s2
	s_addc_u32 s3, s83, s3
	s_add_u32 s2, s2, 0x19800
	s_addc_u32 s3, s3, 0
	s_mov_b32 s7, 0x100000
	buffer_inv sc1
	s_branch .LBB0_904

.LBB0_914:
	s_andn2_b64 vcc, exec, s[4:5]
	s_cbranch_vccz .LBB0_916
	v_mov_b32_e32 v2, 0
	v_mov_b32_e32 v3, 1
	global_store_dword v2, v3, s[82:83] sc1
.LBB0_916:
	s_waitcnt vmcnt(0)
	s_waitcnt vmcnt(0)
.LBB0_917:
	s_or_b64 exec, exec, s[0:1]
	v_ashrrev_i32_e32 v3, 31, v6
	v_lshrrev_b32_e32 v3, 26, v3
	v_add_u32_e32 v3, v6, v3
	v_ashrrev_i32_e32 v7, 6, v3
	v_bfe_i32 v3, v6, 27, 1
	v_lshlrev_b32_e32 v2, 4, v6
	v_lshrrev_b32_e32 v3, 22, v3
	v_add_u32_e32 v3, v2, v3
	v_and_b32_e32 v3, 0xfffffc00, v3
	v_sub_u32_e32 v3, v2, v3
	v_lshrrev_b32_e32 v4, 4, v3
	v_bitop3_b32 v3, v4, v3, 32 bitop3:0x6c
	v_ashrrev_i32_e32 v5, 31, v3
	v_lshrrev_b32_e32 v5, 26, v5
	v_add_u32_e32 v5, v3, v5
	v_ashrrev_i32_e32 v8, 6, v5
	v_and_b32_e32 v5, 0xc0, v5
	v_lshlrev_b32_e32 v4, 3, v7
	v_sub_u32_e32 v3, v3, v5
	v_mov_b32_e32 v5, 1
	v_and_b32_e32 v4, -16, v4
	v_lshlrev_b32_e32 v9, 5, v7
	v_ashrrev_i16_sdwa v3, v5, sext(v3) dst_sel:DWORD dst_unused:UNUSED_PAD src0_sel:DWORD src1_sel:BYTE_0
	v_add_u32_e32 v4, v8, v4
	v_and_b32_e32 v10, 32, v9
	v_bfe_i32 v9, v3, 0, 16
	v_add_u32_e32 v3, v10, v9
	v_lshlrev_b32_e32 v10, 7, v4
	v_add_u32_e32 v2, 0x2000, v2
	s_waitcnt vmcnt(3)
	v_lshl_add_u32 v130, v3, 1, v10
	v_ashrrev_i32_e32 v3, 31, v2
	v_lshrrev_b32_e32 v3, 22, v3
	v_add_u32_e32 v3, v2, v3
	v_ashrrev_i32_e32 v10, 10, v3
	v_mul_i32_i24_e32 v3, 0x400, v10
	v_sub_u32_e32 v2, v2, v3
	v_lshrrev_b32_e32 v3, 4, v2
	s_movk_i32 s2, 0x780
	v_bitop3_b32 v2, v3, v2, 32 bitop3:0x6c
	v_mad_u64_u32 v[132:133], s[0:1], v4, s2, v[130:131]
	v_ashrrev_i32_e32 v4, 31, v2
	v_lshrrev_b32_e32 v4, 26, v4
	v_add_u32_e32 v4, v2, v4
	v_ashrrev_i32_e32 v11, 6, v4
	v_and_b32_e32 v4, 0xc0, v4
	v_lshlrev_b32_e32 v3, 3, v10
	v_sub_u32_e32 v2, v2, v4
	v_and_b32_e32 v3, -16, v3
	v_lshlrev_b32_e32 v12, 5, v10
	v_ashrrev_i16_sdwa v2, v5, sext(v2) dst_sel:DWORD dst_unused:UNUSED_PAD src0_sel:DWORD src1_sel:BYTE_0
	v_add_u32_e32 v3, v11, v3
	v_and_b32_e32 v13, 32, v12
	v_bfe_i32 v12, v2, 0, 16
	v_add_u32_e32 v2, v13, v12
	v_lshlrev_b32_e32 v4, 7, v3
	s_waitcnt vmcnt(2)
	v_lshl_add_u32 v134, v2, 1, v4
	v_mad_u64_u32 v[136:137], s[0:1], v3, s2, v[134:135]
	s_ashr_i32 s5, s19, 6
	s_ashr_i32 s7, s6, 31
	s_bfe_u32 s18, s64, 0x20003
	s_ashr_i32 s4, s19, 8
	s_lshl_b32 s10, s5, 10
	s_lshl_b64 s[0:1], s[6:7], 15
	v_readlane_b32 s2, v254, 24
	v_readlane_b32 s3, v254, 25
	s_add_u32 s0, s2, s0
	s_addc_u32 s1, s3, s1
	s_lshl_b32 s11, s18, 19
	s_add_u32 s15, s82, s11
	s_addc_u32 s17, s83, 0
	s_add_u32 s2, s15, 0x900000
	s_addc_u32 s3, s17, 0
	s_add_i32 s7, s10, 0
	s_add_i32 m0, s7, 0x10000
	s_barrier
	global_load_lds_dwordx4 v132, s[2:3]
	s_add_i32 m0, s7, 0x12000
	s_add_u32 s16, s15, 0x940000
	global_load_lds_dwordx4 v136, s[2:3]
	s_addc_u32 s17, s17, 0
	s_add_i32 m0, s7, 0x14000
	s_add_i32 s20, s7, 0x2000
	global_load_lds_dwordx4 v132, s[16:17]
	s_add_i32 m0, s7, 0x16000
	v_mov_b32_e32 v133, 0
	global_load_lds_dwordx4 v136, s[16:17]
	s_mov_b32 m0, s7
	s_add_u32 s16, s0, 0x4000
	global_load_lds_dwordx4 v130, s[0:1]
	s_mov_b32 m0, s20
	s_addc_u32 s17, s1, 0
	s_add_i32 s21, s7, 0x4000
	global_load_lds_dwordx4 v134, s[0:1]
	s_mov_b32 m0, s21
	s_add_i32 s22, s7, 0x6000
	global_load_lds_dwordx4 v130, s[16:17]
	s_mov_b32 m0, s22
	v_mov_b32_e32 v137, v133
	global_load_lds_dwordx4 v134, s[16:17]
	v_lshl_add_u64 v[4:5], s[2:3], 0, v[132:133]
	v_lshl_add_u64 v[2:3], s[2:3], 0, v[136:137]
	v_mov_b32_e32 v131, v133
	s_cmp_lg_u32 s4, 1
	v_mov_b32_e32 v135, v133
	s_cbranch_scc1 .LBB0_919
	s_barrier

.LBB0_951:
	s_andn2_b64 vcc, exec, s[14:15]
	s_cbranch_vccz .LBB0_957
	s_and_saveexec_b64 s[8:9], s[4:5]
	s_xor_b64 s[4:5], exec, s[8:9]
	s_cbranch_execz .LBB0_954
	s_waitcnt lgkmcnt(0)
.LBB0_954:
	s_or_saveexec_b64 s[8:9], s[4:5]
	s_mov_b64 s[4:5], 0
	s_xor_b64 exec, exec, s[8:9]
	s_cbranch_execz .LBB0_956
	s_and_b32 s6, s6, 0xff
	s_or_b32 s6, s6, 0x700
	v_mov_b32_e32 v1, 0
	v_mov_b32_e32 v0, s6
	global_atomic_cmpswap v1, v[0:1], s[82:83] offset:4
	s_mov_b64 s[4:5], exec
	v_mov_b32_e32 v0, 1
	global_store_dword v1, v0, s[82:83] sc1

.LBB0_958:
	s_waitcnt vmcnt(0) lgkmcnt(0)
	s_and_b64 exec, exec, s[2:3]
	v_cndmask_b32_e64 v0, 0, 1, s[6:7]
	v_mov_b32_e32 v1, 0
	ds_write_b32 v1, v0 offset:10240
